# P6 act_item: 32 dword row loads + 16 dword stores per batch replaced by 8 LDS-DMA dwordx4 loads and 4 dwordx4 stores through wave-private LDS staging
# baseline (speedup 1.0000x reference)
; __device__ __forceinline__ void act_item(int item, u16* UP, const u16* HALO, const float* sconv, const float* wconv, const float* bconv, float* out, int lane) {
;     const int rb = item / 22, cch = item - rb * 22, j0 = cch * 128 + 2 * lane;
;     float wgt[3][2], wvl[3][2], bg[2], bv[2];
; #pragma unroll
;     for (int k = 0; k < 3; ++k) { const f32x2 a = *(const f32x2*)(wconv + k * FF2 + j0), b = *(const f32x2*)(wconv + k * FF2 + FF + j0); wgt[k][0] = a.x; wgt[k][1] = a.y; wvl[k][0] = b.x; wvl[k][1] = b.y; }
;     { const f32x2 a = *(const f32x2*)(bconv + j0), b = *(const f32x2*)(bconv + FF + j0); bg[0] = a.x; bg[1] = a.y; bv[0] = b.x; bv[1] = b.y; }
; __global__ void __launch_bounds__(512, 2) fwd_kernel(Args args) {
;     ...
;     if (IN(6)) {
;         for (int it = gw; it < 264 * 22; it += NGW) act_item(it, UP, HALO, args.in[I_SCONV], args.in[I_WCONV], args.in[I_BCONV], out, lane);
.LBB0_767:
	s_cmp_lt_i32 s94, 7
	s_cselect_b64 s[6:7], -1, 0
	s_add_u32 s12, s92, 0x900000
	s_addc_u32 s13, s93, 0
	s_and_b64 s[28:29], s[6:7], s[0:1]
	s_andn2_b64 vcc, exec, s[28:29]
	s_cbranch_vccnz .LBB0_824
	s_cmpk_gt_i32 s34, 0x16af
	s_cbranch_scc1 .LBB0_819
	s_add_u32 s36, s42, 0x2c00
	s_addc_u32 s37, s43, 0
	s_add_u32 s38, s42, 0x5800
	s_addc_u32 s39, s43, 0
	s_add_u32 s40, s42, 0x8400
	s_addc_u32 s41, s43, 0
	s_add_u32 s46, s42, 0xb000
	s_addc_u32 s47, s43, 0
	s_add_u32 s54, s42, 0xdc00
	v_readlane_b32 s60, v237, 0
	s_addc_u32 s55, s43, 0
	v_readlane_b32 s61, v237, 1
	v_readlane_b32 s62, v237, 2
	v_readlane_b32 s63, v237, 3
	v_readlane_b32 s64, v237, 4
	v_readlane_b32 s65, v237, 5
	s_add_u32 s56, s44, 0x2c00
	v_readlane_b32 s66, v237, 6
	v_readlane_b32 s67, v237, 7
	s_mov_b64 s[60:61], s[64:65]
	s_addc_u32 s57, s45, 0
	s_mov_b64 s[62:63], s[66:67]
	s_add_u32 s3, s62, 0x5300000
	s_addc_u32 s21, s63, 0
	s_add_u32 s33, s62, 0x5358000
	v_readlane_b32 s1, v237, 12
	s_addc_u32 s35, s63, 0
	s_lshl_b32 s0, s2, 10
	s_lshl_b32 s1, s1, 7
	v_lshlrev_b32_e32 v41, 1, v128
	s_add_i32 s0, s0, s1
	v_or_b32_e32 v43, s0, v41
	s_lshl_b32 s70, s14, 10
	v_mov_b32_e32 v0, 0
	s_movk_i32 s71, 0x1000
	s_mov_b32 s72, 0x4300000
	s_mov_b32 s73, 0x4302000
	s_mov_b32 s74, 0x430b000
	s_mov_b32 s75, 0x430d000
	s_mov_b32 s76, 0x4316000
	s_mov_b32 s77, 0x4318000
	s_mov_b32 s78, 0x4321000
	s_mov_b32 s79, 0x4323000
	v_readlane_b32 s101, v237, 12
	v_lshrrev_b32_e32 v100, 4, v128
	v_mul_u32_u24_e32 v100, 0x2c00, v100
	v_and_b32_e32 v101, 15, v128
	s_mul_i32 s101, s101, 0x3000
	v_lshl_add_u32 v100, v101, 4, v100
	v_lshl_add_u32 v101, v128, 2, s101
	v_lshl_add_u32 v102, v128, 4, s101
	s_mov_b32 s80, s34
	s_branch .LBB0_771

; __device__ __forceinline__ float bf2f(unsigned b) { return __uint_as_float(b << 16); }
; __device__ __forceinline__ void act_item(int item, u16* UP, const u16* HALO, const float* sconv, const float* wconv, const float* bconv, float* out, int lane) {
;     const int rb = item / 22, cch = item - rb * 22, j0 = cch * 128 + 2 * lane;
;     float wgt[3][2], wvl[3][2], bg[2], bv[2];
; #pragma unroll
;     for (int k = 0; k < 3; ++k) { const f32x2 a = *(const f32x2*)(wconv + k * FF2 + j0), b = *(const f32x2*)(wconv + k * FF2 + FF + j0); wgt[k][0] = a.x; wgt[k][1] = a.y; wvl[k][0] = b.x; wvl[k][1] = b.y; }
;     { const f32x2 a = *(const f32x2*)(bconv + j0), b = *(const f32x2*)(bconv + FF + j0); bg[0] = a.x; bg[1] = a.y; bv[0] = b.x; bv[1] = b.y; }
;     const bool sample = rb >= 256;
;     float g2[2] = {0.f, 0.f}, g1[2] = {0.f, 0.f}, v2[2] = {0.f, 0.f}, v1[2] = {0.f, 0.f};
;     if (!sample && (rb & 31) != 0) {
;         const unsigned a = *(const unsigned*)(HALO + (size_t)((rb - 1) * 2) * FF2 + j0), b = *(const unsigned*)(HALO + (size_t)((rb - 1) * 2) * FF2 + FF + j0);
;         const unsigned c = *(const unsigned*)(HALO + (size_t)((rb - 1) * 2 + 1) * FF2 + j0), dd = *(const unsigned*)(HALO + (size_t)((rb - 1) * 2 + 1) * FF2 + FF + j0);
;         g2[0] = bf2f(a & 0xffffu); g2[1] = bf2f(a >> 16); v2[0] = bf2f(b & 0xffffu); v2[1] = bf2f(b >> 16);
;         g1[0] = bf2f(c & 0xffffu); g1[1] = bf2f(c >> 16); v1[0] = bf2f(dd & 0xffffu); v1[1] = bf2f(dd >> 16);
;     }
.LBB0_771:
	s_mul_hi_i32 s0, s80, 0x2e8ba2e9
	s_lshr_b32 s1, s0, 31
	s_ashr_i32 s0, s0, 2
	s_add_i32 s0, s0, s1
	s_mul_i32 s1, s0, 0xffffffea
	s_add_i32 s1, s1, s80
	s_lshl_b32 s100, s1, 8
	v_lshl_or_b32 v2, s1, 7, v41
	v_ashrrev_i32_e32 v3, 31, v2
	v_lshlrev_b64 v[16:17], 2, v[2:3]
	v_lshl_add_u64 v[4:5], s[42:43], 0, v[16:17]
	v_lshl_add_u64 v[6:7], s[36:37], 0, v[16:17]
	v_lshl_add_u64 v[8:9], s[38:39], 0, v[16:17]
	v_lshl_add_u64 v[10:11], s[40:41], 0, v[16:17]
	global_load_dwordx2 v[4:5], v[4:5], off
	s_nop 0
	global_load_dwordx2 v[6:7], v[6:7], off
	s_nop 0
	global_load_dwordx2 v[8:9], v[8:9], off
	s_nop 0
	global_load_dwordx2 v[10:11], v[10:11], off
	v_lshl_add_u64 v[12:13], s[46:47], 0, v[16:17]
	v_lshl_add_u64 v[14:15], s[54:55], 0, v[16:17]
	v_lshl_add_u64 v[18:19], s[44:45], 0, v[16:17]
	global_load_dwordx2 v[12:13], v[12:13], off
	s_nop 0
	global_load_dwordx2 v[14:15], v[14:15], off
	v_lshl_add_u64 v[20:21], s[56:57], 0, v[16:17]
	global_load_dwordx2 v[16:17], v[18:19], off
	s_nop 0
	global_load_dwordx2 v[18:19], v[20:21], off
	s_cmpk_gt_i32 s80, 0x15ff
	s_cselect_b64 s[58:59], -1, 0
	s_cmpk_lt_i32 s80, 0x1600
	s_cselect_b64 s[60:61], -1, 0
	s_and_b32 s1, s0, 31
	s_cmp_eq_u32 s1, 0
	s_cselect_b64 s[6:7], -1, 0
	s_or_b64 s[6:7], s[58:59], s[6:7]
	v_mov_b32_e32 v1, v0
	s_and_b64 vcc, exec, s[6:7]
	v_mov_b64_e32 v[50:51], v[0:1]
	v_mov_b64_e32 v[48:49], v[0:1]
	v_mov_b64_e32 v[54:55], v[0:1]
	v_mov_b64_e32 v[52:53], v[0:1]
	s_cbranch_vccnz .LBB0_773
	s_lshl_b32 s62, s0, 1
	s_mul_i32 s7, s0, 0x5800
	s_add_i32 s6, s62, -2
	s_addk_i32 s7, 0xa800
	s_mul_hi_i32 s63, s6, 0x2c00
	s_add_u32 s6, s18, s7
	s_addc_u32 s7, s19, s63
	v_lshlrev_b64 v[20:21], 1, v[2:3]
	v_lshl_add_u64 v[22:23], s[6:7], 0, v[20:21]
	s_add_i32 s6, s62, -1
	s_mul_hi_i32 s7, s6, 0x2c00
	s_mulk_i32 s6, 0x2c00
	s_add_u32 s6, s18, s6
	v_add_co_u32_e32 v24, vcc, 0x1000, v22
	s_addc_u32 s7, s19, s7
	s_nop 0
	v_addc_co_u32_e32 v25, vcc, 0, v23, vcc
	v_lshl_add_u64 v[20:21], s[6:7], 0, v[20:21]
	global_load_dword v1, v[22:23], off
	s_nop 0
	global_load_dword v22, v[24:25], off offset:1536
	global_load_dword v23, v[20:21], off
	v_add_co_u32_e32 v20, vcc, s71, v20
	s_waitcnt vmcnt(0)
	v_lshlrev_b32_e32 v48, 16, v1
	v_addc_co_u32_e32 v21, vcc, 0, v21, vcc
	global_load_dword v20, v[20:21], off offset:1536
	v_and_b32_e32 v49, 0xffff0000, v1
	v_lshlrev_b32_e32 v50, 16, v22
	v_and_b32_e32 v51, 0xffff0000, v22
	v_lshlrev_b32_e32 v52, 16, v23
	v_and_b32_e32 v53, 0xffff0000, v23
	s_waitcnt vmcnt(0)
	v_lshlrev_b32_e32 v54, 16, v20
	v_and_b32_e32 v55, 0xffff0000, v20

; __device__ __forceinline__ unsigned pk2(float lo, float hi) { unsigned r; asm("v_cvt_pk_bf16_f32 %0, %1, %2" : "=v"(r) : "v"(lo), "v"(hi)); return r; }
; __device__ __forceinline__ void act_item(int item, u16* UP, const u16* HALO, const float* sconv, const float* wconv, const float* bconv, float* out, int lane) {
;     ...
;     for (int tb = 0; tb < 64; tb += 16) {
;         unsigned gw[16], vw[16];
; #pragma unroll
;         for (int t = 0; t < 16; ++t) { const size_t row = (size_t)rb * 64 + tb + t; gw[t] = *(const unsigned*)(UP + row * FF2 + j0); vw[t] = *(const unsigned*)(UP + row * FF2 + FF + j0); }
; #pragma unroll
;         for (int t = 0; t < 16; ++t) {
;             const int row = rb * 64 + tb + t;
;             if (sample && (t & 3) == 0) { const int ns = (row - TP) >> 2; const float* s0 = sconv + (size_t)ns * 2 * FF2;
;                 const f32x2 a = *(const f32x2*)(s0 + j0), b = *(const f32x2*)(s0 + FF + j0), c = *(const f32x2*)(s0 + FF2 + j0), dd = *(const f32x2*)(s0 + FF2 + FF + j0);
;                 g2[0] = a.x; g2[1] = a.y; v2[0] = b.x; v2[1] = b.y; g1[0] = c.x; g1[1] = c.y; v1[0] = dd.x; v1[1] = dd.y; }
;     ...
;             *(unsigned*)(UP + (size_t)row * FF2 + j0) = pk2(res[0], res[1]);
.LBB0_774:
	ds_read_b128 v[104:107], v102 offset:8192
	ds_read_b128 v[108:111], v102 offset:9216
	ds_read_b128 v[112:115], v102 offset:10240
	ds_read_b128 v[116:119], v102 offset:11264
	s_add_u32 s98, s64, 0x4300000
	s_addc_u32 s99, s65, 0
	s_add_u32 s98, s98, s100
	s_addc_u32 s99, s99, 0
	s_waitcnt lgkmcnt(3)
	global_store_dwordx4 v100, v[104:107], s[98:99]
	s_add_u32 s98, s98, 0xb000
	s_addc_u32 s99, s99, 0
	s_waitcnt lgkmcnt(2)
	global_store_dwordx4 v100, v[108:111], s[98:99]
	s_add_u32 s98, s98, 0xb000
	s_addc_u32 s99, s99, 0
	s_waitcnt lgkmcnt(1)
	global_store_dwordx4 v100, v[112:115], s[98:99]
	s_add_u32 s98, s98, 0xb000
	s_addc_u32 s99, s99, 0
	s_waitcnt lgkmcnt(0)
	global_store_dwordx4 v100, v[116:119], s[98:99]
	s_add_i32 s0, s83, 16
	s_add_u32 s64, s64, 0x2c000
	s_addc_u32 s65, s65, 0
	s_add_u32 s66, s66, 0x2c000
	s_addc_u32 s67, s67, 0
	s_cmp_lt_u32 s83, 48
	s_mov_b32 s83, s0
	s_cbranch_scc0 .LBB0_770
.LBB0_775:
	s_add_u32 s98, s66, 0x4300000
	s_addc_u32 s99, s67, 0
	s_add_u32 s98, s98, s100
	s_addc_u32 s99, s99, 0
	s_mov_b32 m0, s101
	s_nop 0
	global_load_lds_dwordx4 v100, s[98:99]
	s_add_u32 s98, s98, 0x1600
	s_addc_u32 s99, s99, 0
	s_add_i32 m0, s101, 0x1000
	s_nop 0
	global_load_lds_dwordx4 v100, s[98:99]
	s_add_u32 s98, s98, 0x9a00
	s_addc_u32 s99, s99, 0
	s_add_i32 m0, s101, 0x400
	s_nop 0
	global_load_lds_dwordx4 v100, s[98:99]
	s_add_u32 s98, s98, 0x1600
	s_addc_u32 s99, s99, 0
	s_add_i32 m0, s101, 0x1400
	s_nop 0
	global_load_lds_dwordx4 v100, s[98:99]
	s_add_u32 s98, s98, 0x9a00
	s_addc_u32 s99, s99, 0
	s_add_i32 m0, s101, 0x800
	s_nop 0
	global_load_lds_dwordx4 v100, s[98:99]
	s_add_u32 s98, s98, 0x1600
	s_addc_u32 s99, s99, 0
	s_add_i32 m0, s101, 0x1800
	s_nop 0
	global_load_lds_dwordx4 v100, s[98:99]
	s_add_u32 s98, s98, 0x9a00
	s_addc_u32 s99, s99, 0
	s_add_i32 m0, s101, 0xc00
	s_nop 0
	global_load_lds_dwordx4 v100, s[98:99]
	s_add_u32 s98, s98, 0x1600
	s_addc_u32 s99, s99, 0
	s_add_i32 m0, s101, 0x1c00
	s_nop 0
	global_load_lds_dwordx4 v100, s[98:99]
	v_cndmask_b32_e64 v60, 0, 1, s[58:59]
	v_cmp_ne_u32_e64 s[6:7], 1, v60
	s_andn2_b64 vcc, exec, s[58:59]
	s_cbranch_vccnz .LBB0_777
	s_add_i32 s0, s81, s83
	s_addk_i32 s0, 0xc000
	s_ashr_i32 s0, s0, 2
	s_mul_hi_i32 s1, s0, 0xb000
	s_mul_i32 s0, s0, 0xb000
	s_add_u32 s0, s22, s0
	s_addc_u32 s1, s23, s1
	v_lshl_add_u64 v[48:49], v[2:3], 2, s[0:1]
	v_add_co_u32_e32 v50, vcc, 0x2000, v48
	s_nop 1
	v_addc_co_u32_e32 v51, vcc, 0, v49, vcc
	v_add_co_u32_e32 v52, vcc, 0x5000, v48
	s_nop 1
	v_addc_co_u32_e32 v53, vcc, 0, v49, vcc
	v_add_co_u32_e32 v54, vcc, 0x8000, v48
	s_nop 1
	v_addc_co_u32_e32 v55, vcc, 0, v49, vcc
	global_load_dwordx2 v[48:49], v[48:49], off
	s_nop 0
	global_load_dwordx2 v[50:51], v[50:51], off offset:3072
	s_nop 0
	global_load_dwordx2 v[52:53], v[52:53], off offset:2048
	s_nop 0
	global_load_dwordx2 v[54:55], v[54:55], off offset:1024
; __device__ __forceinline__ float bf2f(unsigned b) { return __uint_as_float(b << 16); }
; __device__ __forceinline__ unsigned pk2(float lo, float hi) { unsigned r; asm("v_cvt_pk_bf16_f32 %0, %1, %2" : "=v"(r) : "v"(lo), "v"(hi)); return r; }
; __device__ __forceinline__ float gelu_t(float x) { return x * __builtin_amdgcn_rcpf(1.f + __expf(-1.5957691216057308f * (x + 0.044715f * x * x * x))); }
; __device__ __forceinline__ void act_item(int item, u16* UP, const u16* HALO, const float* sconv, const float* wconv, const float* bconv, float* out, int lane) {
;     ...
;         for (int t = 0; t < 16; ++t) { const size_t row = (size_t)rb * 64 + tb + t; gw[t] = *(const unsigned*)(UP + row * FF2 + j0); vw[t] = *(const unsigned*)(UP + row * FF2 + FF + j0); }
; #pragma unroll
;         for (int t = 0; t < 16; ++t) {
;             const int row = rb * 64 + tb + t;
;             if (sample && (t & 3) == 0) { const int ns = (row - TP) >> 2; const float* s0 = sconv + (size_t)ns * 2 * FF2;
;                 const f32x2 a = *(const f32x2*)(s0 + j0), b = *(const f32x2*)(s0 + FF + j0), c = *(const f32x2*)(s0 + FF2 + j0), dd = *(const f32x2*)(s0 + FF2 + FF + j0);
;                 g2[0] = a.x; g2[1] = a.y; v2[0] = b.x; v2[1] = b.y; g1[0] = c.x; g1[1] = c.y; v1[0] = dd.x; v1[1] = dd.y; }
;             const float g0[2] = {bf2f(gw[t] & 0xffffu), bf2f(gw[t] >> 16)}, v0[2] = {bf2f(vw[t] & 0xffffu), bf2f(vw[t] >> 16)};
;             float res[2];
; #pragma unroll
;             for (int p = 0; p < 2; ++p) { const float cgv = bg[p] + wgt[0][p] * g2[p] + wgt[1][p] * g1[p] + wgt[2][p] * g0[p];
;                 const float cvv = bv[p] + wvl[0][p] * v2[p] + wvl[1][p] * v1[p] + wvl[2][p] * v0[p]; res[p] = gelu_t(cgv) * cvv;
;                 g2[p] = g1[p]; g1[p] = g0[p]; v2[p] = v1[p]; v1[p] = v0[p]; }
;             *(unsigned*)(UP + (size_t)row * FF2 + j0) = pk2(res[0], res[1]);
.LBB0_777:
	s_waitcnt vmcnt(0)
	ds_read_b32 v47, v101
	ds_read_b32 v46, v101 offset:4096
	ds_read_b32 v58, v101 offset:256
	ds_read_b32 v59, v101 offset:4352
	ds_read_b32 v56, v101 offset:512
	ds_read_b32 v57, v101 offset:4608
	ds_read_b32 v87, v101 offset:768
	ds_read_b32 v88, v101 offset:4864
	ds_read_b32 v86, v101 offset:1024
	ds_read_b32 v85, v101 offset:5120
	ds_read_b32 v83, v101 offset:1280
	ds_read_b32 v84, v101 offset:5376
	ds_read_b32 v81, v101 offset:1536
	ds_read_b32 v82, v101 offset:5632
	ds_read_b32 v79, v101 offset:1792
	ds_read_b32 v80, v101 offset:5888
	ds_read_b32 v78, v101 offset:2048
	ds_read_b32 v77, v101 offset:6144
	ds_read_b32 v75, v101 offset:2304
	ds_read_b32 v76, v101 offset:6400
	ds_read_b32 v73, v101 offset:2560
	ds_read_b32 v74, v101 offset:6656
	ds_read_b32 v71, v101 offset:2816
	ds_read_b32 v72, v101 offset:6912
	ds_read_b32 v70, v101 offset:3072
	ds_read_b32 v69, v101 offset:7168
	ds_read_b32 v66, v101 offset:3328
	ds_read_b32 v67, v101 offset:7424
	ds_read_b32 v64, v101 offset:3584
	ds_read_b32 v65, v101 offset:7680
	ds_read_b32 v1, v101 offset:3840
	ds_read_b32 v68, v101 offset:7936
	s_waitcnt lgkmcnt(0)
	v_lshlrev_b32_e32 v62, 16, v47
	v_and_b32_e32 v63, 0xffff0000, v47
	v_lshlrev_b32_e32 v89, 16, v46
	v_and_b32_e32 v90, 0xffff0000, v46
	v_pk_fma_f32 v[46:47], v[4:5], v[48:49], v[16:17]
	v_pk_fma_f32 v[48:49], v[6:7], v[50:51], v[18:19]
	v_pk_fma_f32 v[46:47], v[8:9], v[52:53], v[46:47]
	v_pk_fma_f32 v[48:49], v[10:11], v[54:55], v[48:49]
	v_fma_f32 v46, v12, v62, v46
	v_fmac_f32_e32 v47, v13, v63
	v_mul_f32_e32 v50, 0x3d372713, v46
	v_mul_f32_e32 v51, 0x3d372713, v47
	v_mul_f32_e32 v50, v46, v50
	v_mul_f32_e32 v51, v47, v51
	v_fma_f32 v50, v46, v50, v46
	v_fma_f32 v51, v47, v51, v47
	v_mul_f32_e32 v50, 0xbfcc422a, v50
	v_mul_f32_e32 v51, 0xbfcc422a, v51
	v_mul_f32_e32 v50, 0x3fb8aa3b, v50
	v_mul_f32_e32 v51, 0x3fb8aa3b, v51
	v_exp_f32_e32 v50, v50
	v_exp_f32_e32 v51, v51
	v_fma_f32 v48, v14, v89, v48
	v_fmac_f32_e32 v49, v15, v90
	v_add_f32_e32 v50, 1.0, v50
	v_add_f32_e32 v51, 1.0, v51
	v_rcp_f32_e32 v50, v50
	v_rcp_f32_e32 v51, v51
	v_pk_fma_f32 v[60:61], v[6:7], v[54:55], v[18:19]
	v_lshlrev_b32_e32 v54, 16, v57
	v_mul_f32_e32 v46, v46, v50
	v_mul_f32_e32 v47, v47, v51
	v_mul_f32_e32 v46, v48, v46
	v_mul_f32_e32 v47, v49, v47
	v_cvt_pk_bf16_f32 v50, v46, v47
	v_lshl_add_u64 v[46:47], s[64:65], 0, v[44:45]
	v_add_co_u32_e32 v48, vcc, s72, v46
	v_lshlrev_b32_e32 v51, 16, v58
	s_nop 0
	v_addc_co_u32_e32 v49, vcc, 0, v47, vcc
	ds_write_b32 v101, v50 offset:8192
	v_lshlrev_b32_e32 v50, 16, v59
	v_and_b32_e32 v49, 0xffff0000, v58
	v_and_b32_e32 v48, 0xffff0000, v59
	v_pk_fma_f32 v[58:59], v[4:5], v[52:53], v[16:17]
	v_and_b32_e32 v52, 0xffff0000, v57
	v_fmac_f32_e32 v59, v9, v63
	v_fmac_f32_e32 v59, v13, v49
	v_fma_f32 v58, v8, v62, v58
	v_mul_f32_e32 v57, 0x3d372713, v59
	v_fmac_f32_e32 v58, v12, v51
	v_mul_f32_e32 v57, v59, v57
	v_lshlrev_b32_e32 v55, 16, v56
	v_and_b32_e32 v53, 0xffff0000, v56
	v_mul_f32_e32 v56, 0x3d372713, v58
	v_fma_f32 v57, v59, v57, v59
	v_mul_f32_e32 v56, v58, v56
	v_mul_f32_e32 v57, 0xbfcc422a, v57
	v_fma_f32 v56, v58, v56, v58
	v_mul_f32_e32 v57, 0x3fb8aa3b, v57
	v_mul_f32_e32 v56, 0xbfcc422a, v56
	v_exp_f32_e32 v57, v57
	v_mul_f32_e32 v56, 0x3fb8aa3b, v56
	v_exp_f32_e32 v56, v56
	v_fma_f32 v60, v10, v89, v60
	v_add_f32_e32 v57, 1.0, v57
	v_rcp_f32_e32 v57, v57
	v_add_f32_e32 v56, 1.0, v56
	v_rcp_f32_e32 v56, v56
	v_fmac_f32_e32 v60, v14, v50
	v_mul_f32_e32 v57, v59, v57
	v_fma_f32 v59, v4, v62, v16
	v_fmac_f32_e32 v59, v8, v51
	v_mul_f32_e32 v56, v58, v56
	v_fmac_f32_e32 v59, v12, v55
	v_mul_f32_e32 v56, v60, v56
	v_mul_f32_e32 v60, 0x3d372713, v59
	v_mul_f32_e32 v60, v59, v60
	v_fmac_f32_e32 v61, v11, v90
	v_fma_f32 v60, v59, v60, v59
	v_fmac_f32_e32 v61, v40, v48
	v_mul_f32_e32 v60, 0xbfcc422a, v60
	v_mul_f32_e32 v57, v61, v57
	v_cvt_pk_bf16_f32 v58, v56, v57
	v_add_co_u32_e32 v56, vcc, s73, v46
	v_mul_f32_e32 v60, 0x3fb8aa3b, v60
	s_nop 0
	v_addc_co_u32_e32 v57, vcc, 0, v47, vcc
	v_exp_f32_e32 v60, v60
	ds_write_b32 v101, v58 offset:8448
	v_fma_f32 v58, v5, v63, v17
	v_fmac_f32_e32 v58, v9, v49
	v_fmac_f32_e32 v58, v13, v53
	v_add_f32_e32 v57, 1.0, v60
	v_mul_f32_e32 v60, 0x3d372713, v58
	v_mul_f32_e32 v60, v58, v60
	v_fma_f32 v60, v58, v60, v58
	v_mul_f32_e32 v60, 0xbfcc422a, v60
	v_rcp_f32_e32 v57, v57
	v_mul_f32_e32 v60, 0x3fb8aa3b, v60
	v_exp_f32_e32 v60, v60
	v_fma_f32 v56, v6, v89, v18
	v_fmac_f32_e32 v56, v10, v50
	v_fmac_f32_e32 v56, v14, v54
	v_mul_f32_e32 v57, v59, v57
	v_mul_f32_e32 v56, v56, v57
	v_add_f32_e32 v57, 1.0, v60
	v_rcp_f32_e32 v57, v57
	v_fma_f32 v59, v7, v90, v19
	v_fmac_f32_e32 v59, v42, v48
	v_fmac_f32_e32 v59, v40, v52
	v_mul_f32_e32 v57, v58, v57
	v_mul_f32_e32 v57, v59, v57
	v_cvt_pk_bf16_f32 v58, v56, v57
	v_add_co_u32_e32 v56, vcc, 0x4305000, v46
	v_mov_b32_e32 v62, v55
	s_nop 0
	v_addc_co_u32_e32 v57, vcc, 0, v47, vcc
	ds_write_b32 v101, v58 offset:8704
	v_mov_b32_e32 v56, v54
	v_mov_b32_e32 v57, v52
	v_mov_b32_e32 v63, v53
	v_cndmask_b32_e64 v58, 0, 1, s[60:61]
	s_mov_b64 s[68:69], -1
	v_cmp_ne_u32_e64 s[0:1], 1, v58
	s_andn2_b64 vcc, exec, s[60:61]
	v_mov_b64_e32 v[58:59], v[62:63]
	v_mov_b64_e32 v[60:61], v[56:57]
	s_cbranch_vccnz .LBB0_779
	v_mov_b32_e32 v58, v55
	v_mov_b32_e32 v59, v53
	v_mov_b32_e32 v60, v54
	v_mov_b32_e32 v61, v52
	s_mov_b64 s[68:69], 0

; __device__ __forceinline__ unsigned pk2(float lo, float hi) { unsigned r; asm("v_cvt_pk_bf16_f32 %0, %1, %2" : "=v"(r) : "v"(lo), "v"(hi)); return r; }
; __device__ __forceinline__ float gelu_t(float x) { return x * __builtin_amdgcn_rcpf(1.f + __expf(-1.5957691216057308f * (x + 0.044715f * x * x * x))); }
; __device__ __forceinline__ void act_item(int item, u16* UP, const u16* HALO, const float* sconv, const float* wconv, const float* bconv, float* out, int lane) {
;     ...
;             for (int p = 0; p < 2; ++p) { const float cgv = bg[p] + wgt[0][p] * g2[p] + wgt[1][p] * g1[p] + wgt[2][p] * g0[p];
;                 const float cvv = bv[p] + wvl[0][p] * v2[p] + wvl[1][p] * v1[p] + wvl[2][p] * v0[p]; res[p] = gelu_t(cgv) * cvv;
;                 g2[p] = g1[p]; g1[p] = g0[p]; v2[p] = v1[p]; v1[p] = v0[p]; }
;             *(unsigned*)(UP + (size_t)row * FF2 + j0) = pk2(res[0], res[1]);
;             if (!sample) { const int tq = row & 2047; if (tq >= 2046) { float* o = out + O_CONVP + ((size_t)(row >> 11) * 2 + (tq - 2046)) * FF2;
;                     *(f32x2*)(o + j0) = (f32x2){g0[0], g0[1]}; *(f32x2*)(o + FF + j0) = (f32x2){v0[0], v0[1]}; } }
;             else if ((t & 3) >= 2) { const int ns = (row - TP) >> 2; float* o = out + O_CONVS + ((size_t)ns * 2 + ((t & 3) - 2)) * FF2;
;                     *(f32x2*)(o + j0) = (f32x2){g0[0], g0[1]}; *(f32x2*)(o + FF + j0) = (f32x2){v0[0], v0[1]}; }
.LBB0_781:
	v_pk_fma_f32 v[50:51], v[26:27], v[50:51], v[24:25]
	v_pk_fma_f32 v[48:49], v[34:35], v[48:49], v[32:33]
	v_lshlrev_b32_e32 v57, 16, v87
	v_lshlrev_b32_e32 v56, 16, v88
	v_and_b32_e32 v63, 0xffff0000, v87
	v_and_b32_e32 v62, 0xffff0000, v88
	v_pk_fma_f32 v[50:51], v[28:29], v[54:55], v[50:51]
	v_pk_fma_f32 v[48:49], v[36:37], v[52:53], v[48:49]
	v_pk_fma_f32 v[50:51], v[30:31], v[56:57], v[50:51]
	v_pk_fma_f32 v[48:49], v[38:39], v[62:63], v[48:49]
	v_mul_f32_e32 v54, 0x3d372713, v51
	v_mul_f32_e32 v52, 0x3d372713, v49
	v_mul_f32_e32 v54, v51, v54
	v_mul_f32_e32 v52, v49, v52
	v_fma_f32 v54, v51, v54, v51
	v_fma_f32 v52, v49, v52, v49
	v_mul_f32_e32 v54, 0xbfcc422a, v54
	v_mul_f32_e32 v52, 0xbfcc422a, v52
	v_mul_f32_e32 v54, 0x3fb8aa3b, v54
	v_mul_f32_e32 v52, 0x3fb8aa3b, v52
	v_exp_f32_e32 v54, v54
	v_exp_f32_e32 v52, v52
	v_add_f32_e32 v53, 1.0, v54
	v_add_f32_e32 v52, 1.0, v52
	v_rcp_f32_e32 v53, v53
	v_rcp_f32_e32 v52, v52
	v_mul_f32_e32 v51, v51, v53
	v_mul_f32_e32 v49, v49, v52
	v_mul_f32_e32 v50, v50, v51
	v_mul_f32_e32 v48, v48, v49
	v_cvt_pk_bf16_f32 v50, v50, v48
	v_add_co_u32_e32 v48, vcc, 0x4308000, v46
	v_mov_b32_e32 v52, v57
	s_nop 0
	v_addc_co_u32_e32 v49, vcc, 0, v47, vcc
	v_mov_b32_e32 v53, v63
	v_mov_b32_e32 v57, v62
	s_and_b64 vcc, exec, s[6:7]
	ds_write_b32 v101, v50 offset:8960
	s_cbranch_vccnz .LBB0_783
	s_add_i32 s68, s81, s83
	s_addk_i32 s68, 0xc003
	s_ashr_i32 s68, s68, 2
	s_mul_hi_i32 s69, s68, 0xb000
	s_mul_i32 s68, s68, 0xb000
	s_add_u32 s68, s33, s68
	s_addc_u32 s69, s35, s69
	v_lshl_add_u64 v[48:49], v[2:3], 2, s[68:69]
	v_add_co_u32_e32 v50, vcc, 0x5000, v48
	s_nop 1
	v_addc_co_u32_e32 v51, vcc, 0, v49, vcc
	v_add_co_u32_e32 v48, vcc, 0x8000, v48
	global_store_dwordx2 v[50:51], v[52:53], off offset:2048
	s_nop 0
	v_addc_co_u32_e32 v49, vcc, 0, v49, vcc
	global_store_dwordx2 v[48:49], v[56:57], off offset:1024

; __device__ __forceinline__ float bf2f(unsigned b) { return __uint_as_float(b << 16); }
; __device__ __forceinline__ unsigned pk2(float lo, float hi) { unsigned r; asm("v_cvt_pk_bf16_f32 %0, %1, %2" : "=v"(r) : "v"(lo), "v"(hi)); return r; }
; __device__ __forceinline__ float gelu_t(float x) { return x * __builtin_amdgcn_rcpf(1.f + __expf(-1.5957691216057308f * (x + 0.044715f * x * x * x))); }
; __device__ __forceinline__ void act_item(int item, u16* UP, const u16* HALO, const float* sconv, const float* wconv, const float* bconv, float* out, int lane) {
;     ...
;         for (int t = 0; t < 16; ++t) {
;             const int row = rb * 64 + tb + t;
;             if (sample && (t & 3) == 0) { const int ns = (row - TP) >> 2; const float* s0 = sconv + (size_t)ns * 2 * FF2;
;                 const f32x2 a = *(const f32x2*)(s0 + j0), b = *(const f32x2*)(s0 + FF + j0), c = *(const f32x2*)(s0 + FF2 + j0), dd = *(const f32x2*)(s0 + FF2 + FF + j0);
;                 g2[0] = a.x; g2[1] = a.y; v2[0] = b.x; v2[1] = b.y; g1[0] = c.x; g1[1] = c.y; v1[0] = dd.x; v1[1] = dd.y; }
;             const float g0[2] = {bf2f(gw[t] & 0xffffu), bf2f(gw[t] >> 16)}, v0[2] = {bf2f(vw[t] & 0xffffu), bf2f(vw[t] >> 16)};
;             float res[2];
; #pragma unroll
;             for (int p = 0; p < 2; ++p) { const float cgv = bg[p] + wgt[0][p] * g2[p] + wgt[1][p] * g1[p] + wgt[2][p] * g0[p];
;                 const float cvv = bv[p] + wvl[0][p] * v2[p] + wvl[1][p] * v1[p] + wvl[2][p] * v0[p]; res[p] = gelu_t(cgv) * cvv;
;                 g2[p] = g1[p]; g1[p] = g0[p]; v2[p] = v1[p]; v1[p] = v0[p]; }
;             *(unsigned*)(UP + (size_t)row * FF2 + j0) = pk2(res[0], res[1]);
.LBB0_785:
	v_pk_fma_f32 v[48:49], v[4:5], v[58:59], v[16:17]
	v_lshlrev_b32_e32 v62, 16, v86
	v_pk_fma_f32 v[48:49], v[8:9], v[52:53], v[48:49]
	v_and_b32_e32 v63, 0xffff0000, v86
	v_fma_f32 v48, v12, v62, v48
	v_mul_f32_e32 v54, 0x3d372713, v48
	v_fmac_f32_e32 v49, v13, v63
	v_mul_f32_e32 v54, v48, v54
	v_mul_f32_e32 v55, 0x3d372713, v49
	v_fma_f32 v54, v48, v54, v48
	v_mul_f32_e32 v55, v49, v55
	v_mul_f32_e32 v54, 0xbfcc422a, v54
	v_fma_f32 v55, v49, v55, v49
	v_mul_f32_e32 v54, 0x3fb8aa3b, v54
	v_mul_f32_e32 v55, 0xbfcc422a, v55
	v_exp_f32_e32 v54, v54
	v_mul_f32_e32 v55, 0x3fb8aa3b, v55
	v_exp_f32_e32 v55, v55
	v_pk_fma_f32 v[50:51], v[6:7], v[60:61], v[18:19]
	v_add_f32_e32 v54, 1.0, v54
	v_rcp_f32_e32 v54, v54
	v_add_f32_e32 v55, 1.0, v55
	v_rcp_f32_e32 v55, v55
	v_lshlrev_b32_e32 v86, 16, v85
	v_pk_fma_f32 v[50:51], v[10:11], v[56:57], v[50:51]
	v_and_b32_e32 v85, 0xffff0000, v85
	v_fma_f32 v50, v14, v86, v50
	v_mul_f32_e32 v48, v48, v54
	v_mul_f32_e32 v48, v50, v48
	v_fmac_f32_e32 v51, v15, v85
	v_mul_f32_e32 v49, v49, v55
	v_mul_f32_e32 v49, v51, v49
	v_cvt_pk_bf16_f32 v50, v48, v49
	v_add_co_u32_e32 v48, vcc, s74, v46
	v_pk_fma_f32 v[58:59], v[4:5], v[52:53], v[16:17]
	s_nop 0
	v_addc_co_u32_e32 v49, vcc, 0, v47, vcc
	v_lshlrev_b32_e32 v51, 16, v83
	v_fma_f32 v58, v8, v62, v58
	ds_write_b32 v101, v50 offset:9216
	v_and_b32_e32 v49, 0xffff0000, v83
	v_fmac_f32_e32 v59, v9, v63
	v_fmac_f32_e32 v58, v12, v51
	v_mul_f32_e32 v60, 0x3d372713, v58
	v_fmac_f32_e32 v59, v13, v49
	v_mul_f32_e32 v60, v58, v60
	v_mul_f32_e32 v61, 0x3d372713, v59
	v_fma_f32 v60, v58, v60, v58
	v_mul_f32_e32 v61, v59, v61
	v_mul_f32_e32 v60, 0xbfcc422a, v60
	v_fma_f32 v61, v59, v61, v59
	v_mul_f32_e32 v60, 0x3fb8aa3b, v60
	v_mul_f32_e32 v61, 0xbfcc422a, v61
	v_exp_f32_e32 v60, v60
	v_mul_f32_e32 v61, 0x3fb8aa3b, v61
	v_exp_f32_e32 v61, v61
	v_pk_fma_f32 v[56:57], v[6:7], v[56:57], v[18:19]
	v_add_f32_e32 v60, 1.0, v60
	v_rcp_f32_e32 v60, v60
	v_add_f32_e32 v61, 1.0, v61
	v_rcp_f32_e32 v61, v61
	v_lshlrev_b32_e32 v50, 16, v84
	v_fma_f32 v56, v10, v86, v56
	v_fmac_f32_e32 v56, v14, v50
	v_mul_f32_e32 v58, v58, v60
	v_mul_f32_e32 v56, v56, v58
	v_mul_f32_e32 v58, v59, v61
	v_fma_f32 v59, v4, v62, v16
	v_lshlrev_b32_e32 v55, 16, v81
	v_fmac_f32_e32 v59, v8, v51
	v_fmac_f32_e32 v59, v12, v55
	v_mul_f32_e32 v60, 0x3d372713, v59
	v_mul_f32_e32 v60, v59, v60
	v_and_b32_e32 v48, 0xffff0000, v84
	v_fmac_f32_e32 v57, v11, v85
	v_fma_f32 v60, v59, v60, v59
	v_fmac_f32_e32 v57, v40, v48
	v_mul_f32_e32 v60, 0xbfcc422a, v60
	v_mul_f32_e32 v57, v57, v58
	v_cvt_pk_bf16_f32 v58, v56, v57
	v_add_co_u32_e32 v56, vcc, s75, v46
	v_mul_f32_e32 v60, 0x3fb8aa3b, v60
	s_nop 0
	v_addc_co_u32_e32 v57, vcc, 0, v47, vcc
	v_exp_f32_e32 v60, v60
	ds_write_b32 v101, v58 offset:9472
	v_fma_f32 v58, v5, v63, v17
	v_and_b32_e32 v53, 0xffff0000, v81
	v_fmac_f32_e32 v58, v9, v49
	v_fmac_f32_e32 v58, v13, v53
	v_add_f32_e32 v57, 1.0, v60
	v_mul_f32_e32 v60, 0x3d372713, v58
	v_mul_f32_e32 v60, v58, v60
	v_fma_f32 v60, v58, v60, v58
	v_mul_f32_e32 v60, 0xbfcc422a, v60
	v_rcp_f32_e32 v57, v57
	v_mul_f32_e32 v60, 0x3fb8aa3b, v60
	v_exp_f32_e32 v60, v60
	v_fma_f32 v56, v6, v86, v18
	v_lshlrev_b32_e32 v54, 16, v82
	v_fmac_f32_e32 v56, v10, v50
	v_fmac_f32_e32 v56, v14, v54
	v_mul_f32_e32 v57, v59, v57
	v_mul_f32_e32 v56, v56, v57
	v_add_f32_e32 v57, 1.0, v60
	v_rcp_f32_e32 v57, v57
	v_fma_f32 v59, v7, v85, v19
	v_and_b32_e32 v52, 0xffff0000, v82
	v_fmac_f32_e32 v59, v42, v48
	v_fmac_f32_e32 v59, v40, v52
	v_mul_f32_e32 v57, v58, v57
	v_mul_f32_e32 v57, v59, v57
	v_cvt_pk_bf16_f32 v58, v56, v57
	v_add_co_u32_e32 v56, vcc, 0x4310000, v46
	v_mov_b32_e32 v59, v52
	s_nop 0
	v_addc_co_u32_e32 v57, vcc, 0, v47, vcc
	ds_write_b32 v101, v58 offset:9728
	v_mov_b32_e32 v58, v54
	v_mov_b32_e32 v62, v55
	v_mov_b32_e32 v63, v53
	s_mov_b64 s[68:69], -1
	s_and_b64 vcc, exec, s[0:1]
	v_mov_b64_e32 v[56:57], v[62:63]
	v_mov_b64_e32 v[60:61], v[58:59]
	s_cbranch_vccnz .LBB0_787
	v_mov_b32_e32 v56, v55
	v_mov_b32_e32 v57, v53
	v_mov_b32_e32 v60, v54
	v_mov_b32_e32 v61, v52
	s_mov_b64 s[68:69], 0

; __device__ __forceinline__ unsigned pk2(float lo, float hi) { unsigned r; asm("v_cvt_pk_bf16_f32 %0, %1, %2" : "=v"(r) : "v"(lo), "v"(hi)); return r; }
; __device__ __forceinline__ float gelu_t(float x) { return x * __builtin_amdgcn_rcpf(1.f + __expf(-1.5957691216057308f * (x + 0.044715f * x * x * x))); }
; __device__ __forceinline__ void act_item(int item, u16* UP, const u16* HALO, const float* sconv, const float* wconv, const float* bconv, float* out, int lane) {
;     ...
;             for (int p = 0; p < 2; ++p) { const float cgv = bg[p] + wgt[0][p] * g2[p] + wgt[1][p] * g1[p] + wgt[2][p] * g0[p];
;                 const float cvv = bv[p] + wvl[0][p] * v2[p] + wvl[1][p] * v1[p] + wvl[2][p] * v0[p]; res[p] = gelu_t(cgv) * cvv;
;                 g2[p] = g1[p]; g1[p] = g0[p]; v2[p] = v1[p]; v1[p] = v0[p]; }
;             *(unsigned*)(UP + (size_t)row * FF2 + j0) = pk2(res[0], res[1]);
;             if (!sample) { const int tq = row & 2047; if (tq >= 2046) { float* o = out + O_CONVP + ((size_t)(row >> 11) * 2 + (tq - 2046)) * FF2;
;                     *(f32x2*)(o + j0) = (f32x2){g0[0], g0[1]}; *(f32x2*)(o + FF + j0) = (f32x2){v0[0], v0[1]}; } }
;             else if ((t & 3) >= 2) { const int ns = (row - TP) >> 2; float* o = out + O_CONVS + ((size_t)ns * 2 + ((t & 3) - 2)) * FF2;
;                     *(f32x2*)(o + j0) = (f32x2){g0[0], g0[1]}; *(f32x2*)(o + FF + j0) = (f32x2){v0[0], v0[1]}; }
.LBB0_789:
	v_pk_fma_f32 v[48:49], v[34:35], v[48:49], v[32:33]
	v_and_b32_e32 v63, 0xffff0000, v79
	v_and_b32_e32 v62, 0xffff0000, v80
	v_pk_fma_f32 v[50:51], v[26:27], v[50:51], v[24:25]
	v_pk_fma_f32 v[48:49], v[36:37], v[52:53], v[48:49]
	v_lshlrev_b32_e32 v59, 16, v79
	v_lshlrev_b32_e32 v58, 16, v80
	v_pk_fma_f32 v[50:51], v[28:29], v[54:55], v[50:51]
	v_pk_fma_f32 v[48:49], v[38:39], v[62:63], v[48:49]
	v_pk_fma_f32 v[50:51], v[30:31], v[58:59], v[50:51]
	v_mul_f32_e32 v52, 0x3d372713, v49
	v_mul_f32_e32 v54, 0x3d372713, v51
	v_mul_f32_e32 v52, v49, v52
	v_mul_f32_e32 v54, v51, v54
	v_fma_f32 v52, v49, v52, v49
	v_fma_f32 v54, v51, v54, v51
	v_mul_f32_e32 v52, 0xbfcc422a, v52
	v_mul_f32_e32 v54, 0xbfcc422a, v54
	v_mul_f32_e32 v52, 0x3fb8aa3b, v52
	v_mul_f32_e32 v54, 0x3fb8aa3b, v54
	v_exp_f32_e32 v52, v52
	v_exp_f32_e32 v54, v54
	v_add_f32_e32 v52, 1.0, v52
	v_add_f32_e32 v53, 1.0, v54
	v_rcp_f32_e32 v52, v52
	v_rcp_f32_e32 v53, v53
	v_mul_f32_e32 v49, v49, v52
	v_mul_f32_e32 v51, v51, v53
	v_mul_f32_e32 v48, v48, v49
	v_mul_f32_e32 v53, v50, v51
	v_cvt_pk_bf16_f32 v52, v53, v48
	v_add_co_u32_e32 v48, vcc, 0x4313000, v46
	v_mov_b32_e32 v50, v59
	s_nop 0
	v_addc_co_u32_e32 v49, vcc, 0, v47, vcc
	v_mov_b32_e32 v51, v63
	v_mov_b32_e32 v59, v62
	s_and_b64 vcc, exec, s[6:7]
	ds_write_b32 v101, v52 offset:9984
	s_cbranch_vccnz .LBB0_791
	s_add_i32 s68, s81, s83
	s_addk_i32 s68, 0xc007
	s_ashr_i32 s68, s68, 2
	s_mul_hi_i32 s69, s68, 0xb000
	s_mul_i32 s68, s68, 0xb000
	s_add_u32 s68, s33, s68
	s_addc_u32 s69, s35, s69
	v_lshl_add_u64 v[48:49], v[2:3], 2, s[68:69]
	v_add_co_u32_e32 v52, vcc, 0x5000, v48
	s_nop 1
	v_addc_co_u32_e32 v53, vcc, 0, v49, vcc
	v_add_co_u32_e32 v48, vcc, 0x8000, v48
	global_store_dwordx2 v[52:53], v[50:51], off offset:2048
	s_nop 0
	v_addc_co_u32_e32 v49, vcc, 0, v49, vcc
	global_store_dwordx2 v[48:49], v[58:59], off offset:1024

; __device__ __forceinline__ float bf2f(unsigned b) { return __uint_as_float(b << 16); }
; __device__ __forceinline__ unsigned pk2(float lo, float hi) { unsigned r; asm("v_cvt_pk_bf16_f32 %0, %1, %2" : "=v"(r) : "v"(lo), "v"(hi)); return r; }
; __device__ __forceinline__ float gelu_t(float x) { return x * __builtin_amdgcn_rcpf(1.f + __expf(-1.5957691216057308f * (x + 0.044715f * x * x * x))); }
; __device__ __forceinline__ void act_item(int item, u16* UP, const u16* HALO, const float* sconv, const float* wconv, const float* bconv, float* out, int lane) {
;     ...
;         for (int t = 0; t < 16; ++t) {
;             const int row = rb * 64 + tb + t;
;             if (sample && (t & 3) == 0) { const int ns = (row - TP) >> 2; const float* s0 = sconv + (size_t)ns * 2 * FF2;
;                 const f32x2 a = *(const f32x2*)(s0 + j0), b = *(const f32x2*)(s0 + FF + j0), c = *(const f32x2*)(s0 + FF2 + j0), dd = *(const f32x2*)(s0 + FF2 + FF + j0);
;                 g2[0] = a.x; g2[1] = a.y; v2[0] = b.x; v2[1] = b.y; g1[0] = c.x; g1[1] = c.y; v1[0] = dd.x; v1[1] = dd.y; }
;             const float g0[2] = {bf2f(gw[t] & 0xffffu), bf2f(gw[t] >> 16)}, v0[2] = {bf2f(vw[t] & 0xffffu), bf2f(vw[t] >> 16)};
;             float res[2];
; #pragma unroll
;             for (int p = 0; p < 2; ++p) { const float cgv = bg[p] + wgt[0][p] * g2[p] + wgt[1][p] * g1[p] + wgt[2][p] * g0[p];
;                 const float cvv = bv[p] + wvl[0][p] * v2[p] + wvl[1][p] * v1[p] + wvl[2][p] * v0[p]; res[p] = gelu_t(cgv) * cvv;
;                 g2[p] = g1[p]; g1[p] = g0[p]; v2[p] = v1[p]; v1[p] = v0[p]; }
;             *(unsigned*)(UP + (size_t)row * FF2 + j0) = pk2(res[0], res[1]);
.LBB0_793:
	v_pk_fma_f32 v[48:49], v[4:5], v[56:57], v[16:17]
	v_lshlrev_b32_e32 v54, 16, v78
	v_pk_fma_f32 v[48:49], v[8:9], v[50:51], v[48:49]
	v_and_b32_e32 v55, 0xffff0000, v78
	v_fma_f32 v48, v12, v54, v48
	v_mul_f32_e32 v56, 0x3d372713, v48
	v_fmac_f32_e32 v49, v13, v55
	v_mul_f32_e32 v56, v48, v56
	v_mul_f32_e32 v57, 0x3d372713, v49
	v_fma_f32 v56, v48, v56, v48
	v_mul_f32_e32 v57, v49, v57
	v_mul_f32_e32 v56, 0xbfcc422a, v56
	v_fma_f32 v57, v49, v57, v49
	v_mul_f32_e32 v56, 0x3fb8aa3b, v56
	v_mul_f32_e32 v57, 0xbfcc422a, v57
	v_exp_f32_e32 v56, v56
	v_mul_f32_e32 v57, 0x3fb8aa3b, v57
	v_exp_f32_e32 v57, v57
	v_pk_fma_f32 v[52:53], v[6:7], v[60:61], v[18:19]
	v_add_f32_e32 v56, 1.0, v56
	v_rcp_f32_e32 v56, v56
	v_add_f32_e32 v57, 1.0, v57
	v_rcp_f32_e32 v57, v57
	v_lshlrev_b32_e32 v62, 16, v77
	v_pk_fma_f32 v[52:53], v[10:11], v[58:59], v[52:53]
	v_and_b32_e32 v63, 0xffff0000, v77
	v_fma_f32 v52, v14, v62, v52
	v_mul_f32_e32 v48, v48, v56
	v_mul_f32_e32 v48, v52, v48
	v_fmac_f32_e32 v53, v15, v63
	v_mul_f32_e32 v49, v49, v57
	v_mul_f32_e32 v49, v53, v49
	v_cvt_pk_bf16_f32 v52, v48, v49
	v_add_co_u32_e32 v48, vcc, s76, v46
	v_pk_fma_f32 v[50:51], v[4:5], v[50:51], v[16:17]
	s_nop 0
	v_addc_co_u32_e32 v49, vcc, 0, v47, vcc
	ds_write_b32 v101, v52 offset:10240
	v_and_b32_e32 v49, 0xffff0000, v75
	v_fmac_f32_e32 v51, v9, v55
	v_fmac_f32_e32 v51, v13, v49
	v_pk_fma_f32 v[52:53], v[6:7], v[58:59], v[18:19]
	v_lshlrev_b32_e32 v60, 16, v74
	v_and_b32_e32 v58, 0xffff0000, v74
	v_mul_f32_e32 v74, 0x3d372713, v51
	v_mul_f32_e32 v74, v51, v74
	v_fma_f32 v74, v51, v74, v51
	v_mul_f32_e32 v74, 0xbfcc422a, v74
	v_lshlrev_b32_e32 v57, 16, v75
	v_fma_f32 v50, v8, v54, v50
	v_mul_f32_e32 v74, 0x3fb8aa3b, v74
	v_fmac_f32_e32 v50, v12, v57
	v_exp_f32_e32 v74, v74
	v_lshlrev_b32_e32 v61, 16, v73
	v_and_b32_e32 v59, 0xffff0000, v73
	v_mul_f32_e32 v73, 0x3d372713, v50
	v_mul_f32_e32 v73, v50, v73
	v_fma_f32 v73, v50, v73, v50
	v_mul_f32_e32 v73, 0xbfcc422a, v73
	v_add_f32_e32 v74, 1.0, v74
	v_mul_f32_e32 v73, 0x3fb8aa3b, v73
	v_rcp_f32_e32 v74, v74
	v_exp_f32_e32 v73, v73
	v_and_b32_e32 v48, 0xffff0000, v76
	v_fmac_f32_e32 v53, v11, v63
	v_fmac_f32_e32 v53, v40, v48
	v_mul_f32_e32 v51, v51, v74
	v_add_f32_e32 v73, 1.0, v73
	v_mul_f32_e32 v51, v53, v51
	v_fma_f32 v53, v4, v54, v16
	v_rcp_f32_e32 v73, v73
	v_fmac_f32_e32 v53, v8, v57
	v_fmac_f32_e32 v53, v12, v61
	v_mul_f32_e32 v54, 0x3d372713, v53
	v_lshlrev_b32_e32 v56, 16, v76
	v_fma_f32 v52, v10, v62, v52
	v_mul_f32_e32 v54, v53, v54
	v_fmac_f32_e32 v52, v14, v56
	v_mul_f32_e32 v50, v50, v73
	v_fma_f32 v54, v53, v54, v53
	v_mul_f32_e32 v50, v52, v50
	v_mul_f32_e32 v54, 0xbfcc422a, v54
	v_cvt_pk_bf16_f32 v52, v50, v51
	v_add_co_u32_e32 v50, vcc, s77, v46
	v_mul_f32_e32 v54, 0x3fb8aa3b, v54
	s_nop 0
	v_addc_co_u32_e32 v51, vcc, 0, v47, vcc
	v_exp_f32_e32 v54, v54
	ds_write_b32 v101, v52 offset:10496
	v_fma_f32 v52, v5, v55, v17
	v_fmac_f32_e32 v52, v9, v49
	v_fmac_f32_e32 v52, v13, v59
	v_add_f32_e32 v51, 1.0, v54
	v_mul_f32_e32 v54, 0x3d372713, v52
	v_mul_f32_e32 v54, v52, v54
	v_fma_f32 v54, v52, v54, v52
	v_mul_f32_e32 v54, 0xbfcc422a, v54
	v_rcp_f32_e32 v51, v51
	v_mul_f32_e32 v54, 0x3fb8aa3b, v54
	v_exp_f32_e32 v54, v54
	v_fma_f32 v50, v6, v62, v18
	v_fmac_f32_e32 v50, v10, v56
	v_fmac_f32_e32 v50, v14, v60
	v_mul_f32_e32 v51, v53, v51
	v_mul_f32_e32 v50, v50, v51
	v_add_f32_e32 v51, 1.0, v54
	v_rcp_f32_e32 v51, v51
	v_fma_f32 v53, v7, v63, v19
	v_fmac_f32_e32 v53, v42, v48
	v_fmac_f32_e32 v53, v40, v58
	v_mul_f32_e32 v51, v52, v51
	v_mul_f32_e32 v51, v53, v51
	v_cvt_pk_bf16_f32 v52, v50, v51
	v_add_co_u32_e32 v50, vcc, 0x431b000, v46
	v_mov_b32_e32 v62, v61
	s_nop 0
	v_addc_co_u32_e32 v51, vcc, 0, v47, vcc
	ds_write_b32 v101, v52 offset:10752
	v_mov_b32_e32 v50, v60
	v_mov_b32_e32 v51, v58
	v_mov_b32_e32 v63, v59
	s_mov_b64 s[68:69], -1
	s_and_b64 vcc, exec, s[0:1]
	v_mov_b64_e32 v[52:53], v[62:63]
	v_mov_b64_e32 v[54:55], v[50:51]
	s_cbranch_vccnz .LBB0_795
	v_mov_b32_e32 v52, v61
	v_mov_b32_e32 v53, v59
	v_mov_b32_e32 v54, v60
	v_mov_b32_e32 v55, v58
	s_mov_b64 s[68:69], 0

; __device__ __forceinline__ unsigned pk2(float lo, float hi) { unsigned r; asm("v_cvt_pk_bf16_f32 %0, %1, %2" : "=v"(r) : "v"(lo), "v"(hi)); return r; }
; __device__ __forceinline__ float gelu_t(float x) { return x * __builtin_amdgcn_rcpf(1.f + __expf(-1.5957691216057308f * (x + 0.044715f * x * x * x))); }
; __device__ __forceinline__ void act_item(int item, u16* UP, const u16* HALO, const float* sconv, const float* wconv, const float* bconv, float* out, int lane) {
;     ...
;             for (int p = 0; p < 2; ++p) { const float cgv = bg[p] + wgt[0][p] * g2[p] + wgt[1][p] * g1[p] + wgt[2][p] * g0[p];
;                 const float cvv = bv[p] + wvl[0][p] * v2[p] + wvl[1][p] * v1[p] + wvl[2][p] * v0[p]; res[p] = gelu_t(cgv) * cvv;
;                 g2[p] = g1[p]; g1[p] = g0[p]; v2[p] = v1[p]; v1[p] = v0[p]; }
;             *(unsigned*)(UP + (size_t)row * FF2 + j0) = pk2(res[0], res[1]);
;             if (!sample) { const int tq = row & 2047; if (tq >= 2046) { float* o = out + O_CONVP + ((size_t)(row >> 11) * 2 + (tq - 2046)) * FF2;
;                     *(f32x2*)(o + j0) = (f32x2){g0[0], g0[1]}; *(f32x2*)(o + FF + j0) = (f32x2){v0[0], v0[1]}; } }
;             else if ((t & 3) >= 2) { const int ns = (row - TP) >> 2; float* o = out + O_CONVS + ((size_t)ns * 2 + ((t & 3) - 2)) * FF2;
;                     *(f32x2*)(o + j0) = (f32x2){g0[0], g0[1]}; *(f32x2*)(o + FF + j0) = (f32x2){v0[0], v0[1]}; }
.LBB0_797:
	v_pk_fma_f32 v[56:57], v[26:27], v[56:57], v[24:25]
	v_lshlrev_b32_e32 v51, 16, v71
	v_lshlrev_b32_e32 v50, 16, v72
	v_pk_fma_f32 v[56:57], v[28:29], v[60:61], v[56:57]
	v_pk_fma_f32 v[48:49], v[34:35], v[48:49], v[32:33]
	v_and_b32_e32 v63, 0xffff0000, v71
	v_and_b32_e32 v62, 0xffff0000, v72
	v_pk_fma_f32 v[56:57], v[30:31], v[50:51], v[56:57]
	v_pk_fma_f32 v[48:49], v[36:37], v[58:59], v[48:49]
	v_mul_f32_e32 v60, 0x3d372713, v57
	v_pk_fma_f32 v[48:49], v[38:39], v[62:63], v[48:49]
	v_mul_f32_e32 v60, v57, v60
	v_mul_f32_e32 v58, 0x3d372713, v49
	v_fma_f32 v60, v57, v60, v57
	v_mul_f32_e32 v58, v49, v58
	v_mul_f32_e32 v60, 0xbfcc422a, v60
	v_fma_f32 v58, v49, v58, v49
	v_mul_f32_e32 v60, 0x3fb8aa3b, v60
	v_mul_f32_e32 v58, 0xbfcc422a, v58
	v_exp_f32_e32 v60, v60
	v_mul_f32_e32 v58, 0x3fb8aa3b, v58
	v_exp_f32_e32 v58, v58
	v_add_f32_e32 v59, 1.0, v60
	v_rcp_f32_e32 v59, v59
	v_add_f32_e32 v58, 1.0, v58
	v_rcp_f32_e32 v58, v58
	v_mul_f32_e32 v57, v57, v59
	v_mul_f32_e32 v56, v56, v57
	v_mul_f32_e32 v49, v49, v58
	v_mul_f32_e32 v57, v48, v49
	v_cvt_pk_bf16_f32 v58, v56, v57
	v_add_co_u32_e32 v56, vcc, 0x431e000, v46
	v_mov_b32_e32 v48, v51
	s_nop 0
	v_addc_co_u32_e32 v57, vcc, 0, v47, vcc
	v_mov_b32_e32 v49, v63
	v_mov_b32_e32 v51, v62
	s_and_b64 vcc, exec, s[6:7]
	ds_write_b32 v101, v58 offset:11008
	s_cbranch_vccnz .LBB0_812
	s_add_i32 s6, s81, s83
	s_addk_i32 s6, 0xc00b
	s_ashr_i32 s6, s6, 2
	s_mul_hi_i32 s7, s6, 0xb000
	s_mul_i32 s6, s6, 0xb000
	s_add_u32 s6, s33, s6
	s_addc_u32 s7, s35, s7
	v_lshl_add_u64 v[56:57], v[2:3], 2, s[6:7]
	v_add_co_u32_e32 v58, vcc, 0x5000, v56
	s_nop 1
	v_addc_co_u32_e32 v59, vcc, 0, v57, vcc
	v_add_co_u32_e32 v56, vcc, 0x8000, v56
	global_store_dwordx2 v[58:59], v[48:49], off offset:2048
	s_nop 0
	v_addc_co_u32_e32 v57, vcc, 0, v57, vcc
	global_store_dwordx2 v[56:57], v[50:51], off offset:1024
	s_and_b64 vcc, exec, s[0:1]
	s_mov_b64 s[6:7], -1
	s_cbranch_vccz .LBB0_813

; __device__ __forceinline__ float bf2f(unsigned b) { return __uint_as_float(b << 16); }
; __device__ __forceinline__ unsigned pk2(float lo, float hi) { unsigned r; asm("v_cvt_pk_bf16_f32 %0, %1, %2" : "=v"(r) : "v"(lo), "v"(hi)); return r; }
; __device__ __forceinline__ float gelu_t(float x) { return x * __builtin_amdgcn_rcpf(1.f + __expf(-1.5957691216057308f * (x + 0.044715f * x * x * x))); }
; __device__ __forceinline__ void act_item(int item, u16* UP, const u16* HALO, const float* sconv, const float* wconv, const float* bconv, float* out, int lane) {
;     ...
;         for (int t = 0; t < 16; ++t) {
;             const int row = rb * 64 + tb + t;
;             if (sample && (t & 3) == 0) { const int ns = (row - TP) >> 2; const float* s0 = sconv + (size_t)ns * 2 * FF2;
;                 const f32x2 a = *(const f32x2*)(s0 + j0), b = *(const f32x2*)(s0 + FF + j0), c = *(const f32x2*)(s0 + FF2 + j0), dd = *(const f32x2*)(s0 + FF2 + FF + j0);
;                 g2[0] = a.x; g2[1] = a.y; v2[0] = b.x; v2[1] = b.y; g1[0] = c.x; g1[1] = c.y; v1[0] = dd.x; v1[1] = dd.y; }
;             const float g0[2] = {bf2f(gw[t] & 0xffffu), bf2f(gw[t] >> 16)}, v0[2] = {bf2f(vw[t] & 0xffffu), bf2f(vw[t] >> 16)};
;             float res[2];
; #pragma unroll
;             for (int p = 0; p < 2; ++p) { const float cgv = bg[p] + wgt[0][p] * g2[p] + wgt[1][p] * g1[p] + wgt[2][p] * g0[p];
;                 const float cvv = bv[p] + wvl[0][p] * v2[p] + wvl[1][p] * v1[p] + wvl[2][p] * v0[p]; res[p] = gelu_t(cgv) * cvv;
;                 g2[p] = g1[p]; g1[p] = g0[p]; v2[p] = v1[p]; v1[p] = v0[p]; }
;             *(unsigned*)(UP + (size_t)row * FF2 + j0) = pk2(res[0], res[1]);
.LBB0_801:
	v_pk_fma_f32 v[52:53], v[4:5], v[52:53], v[16:17]
	v_lshlrev_b32_e32 v71, 16, v70
	v_pk_fma_f32 v[52:53], v[8:9], v[48:49], v[52:53]
	v_and_b32_e32 v70, 0xffff0000, v70
	v_fma_f32 v52, v12, v71, v52
	v_mul_f32_e32 v56, 0x3d372713, v52
	v_fmac_f32_e32 v53, v13, v70
	v_mul_f32_e32 v56, v52, v56
	v_mul_f32_e32 v57, 0x3d372713, v53
	v_fma_f32 v56, v52, v56, v52
	v_mul_f32_e32 v57, v53, v57
	v_mul_f32_e32 v56, 0xbfcc422a, v56
	v_fma_f32 v57, v53, v57, v53
	v_mul_f32_e32 v56, 0x3fb8aa3b, v56
	v_mul_f32_e32 v57, 0xbfcc422a, v57
	v_exp_f32_e32 v56, v56
	v_mul_f32_e32 v57, 0x3fb8aa3b, v57
	v_exp_f32_e32 v57, v57
	v_pk_fma_f32 v[54:55], v[6:7], v[54:55], v[18:19]
	v_add_f32_e32 v56, 1.0, v56
	v_rcp_f32_e32 v56, v56
	v_add_f32_e32 v57, 1.0, v57
	v_rcp_f32_e32 v57, v57
	v_lshlrev_b32_e32 v72, 16, v69
	v_pk_fma_f32 v[54:55], v[10:11], v[50:51], v[54:55]
	v_and_b32_e32 v69, 0xffff0000, v69
	v_fma_f32 v54, v14, v72, v54
	v_mul_f32_e32 v52, v52, v56
	v_mul_f32_e32 v52, v54, v52
	v_fmac_f32_e32 v55, v15, v69
	v_mul_f32_e32 v53, v53, v57
	v_pk_fma_f32 v[48:49], v[4:5], v[48:49], v[16:17]
	v_mul_f32_e32 v53, v55, v53
	v_cvt_pk_bf16_f32 v54, v52, v53
	v_add_co_u32_e32 v52, vcc, s78, v46
	v_and_b32_e32 v57, 0xffff0000, v66
	v_fmac_f32_e32 v49, v9, v70
	v_addc_co_u32_e32 v53, vcc, 0, v47, vcc
	v_fmac_f32_e32 v49, v13, v57
	ds_write_b32 v101, v54 offset:11264
	v_mul_f32_e32 v53, 0x3d372713, v49
	v_mul_f32_e32 v53, v49, v53
	v_lshlrev_b32_e32 v59, 16, v66
	v_fma_f32 v48, v8, v71, v48
	v_fma_f32 v53, v49, v53, v49
	v_fmac_f32_e32 v48, v12, v59
	v_mul_f32_e32 v53, 0xbfcc422a, v53
	v_mul_f32_e32 v52, 0x3d372713, v48
	v_mul_f32_e32 v53, 0x3fb8aa3b, v53
	v_mul_f32_e32 v52, v48, v52
	v_exp_f32_e32 v53, v53
	v_fma_f32 v52, v48, v52, v48
	v_mul_f32_e32 v52, 0xbfcc422a, v52
	v_mul_f32_e32 v52, 0x3fb8aa3b, v52
	v_exp_f32_e32 v52, v52
	v_add_f32_e32 v53, 1.0, v53
	v_rcp_f32_e32 v53, v53
	v_pk_fma_f32 v[50:51], v[6:7], v[50:51], v[18:19]
	v_and_b32_e32 v56, 0xffff0000, v67
	v_fmac_f32_e32 v51, v11, v69
	v_add_f32_e32 v52, 1.0, v52
	v_rcp_f32_e32 v52, v52
	v_fmac_f32_e32 v51, v40, v56
	v_mul_f32_e32 v49, v49, v53
	v_mul_f32_e32 v49, v51, v49
	v_fma_f32 v51, v4, v71, v16
	v_lshlrev_b32_e32 v63, 16, v64
	v_fmac_f32_e32 v51, v8, v59
	v_fmac_f32_e32 v51, v12, v63
	v_mul_f32_e32 v48, v48, v52
	v_mul_f32_e32 v52, 0x3d372713, v51
	v_lshlrev_b32_e32 v58, 16, v67
	v_fma_f32 v50, v10, v72, v50
	v_mul_f32_e32 v52, v51, v52
	v_fmac_f32_e32 v50, v14, v58
	v_fma_f32 v52, v51, v52, v51
	v_mul_f32_e32 v48, v50, v48
	v_mul_f32_e32 v52, 0xbfcc422a, v52
	v_cvt_pk_bf16_f32 v50, v48, v49
	v_add_co_u32_e32 v48, vcc, s79, v46
	v_mul_f32_e32 v52, 0x3fb8aa3b, v52
	s_nop 0
	v_addc_co_u32_e32 v49, vcc, 0, v47, vcc
	v_exp_f32_e32 v52, v52
	ds_write_b32 v101, v50 offset:11520
	v_fma_f32 v50, v5, v70, v17
	v_and_b32_e32 v61, 0xffff0000, v64
	v_fmac_f32_e32 v50, v9, v57
	v_fmac_f32_e32 v50, v13, v61
	v_add_f32_e32 v49, 1.0, v52
	v_mul_f32_e32 v52, 0x3d372713, v50
	v_mul_f32_e32 v52, v50, v52
	v_fma_f32 v52, v50, v52, v50
	v_mul_f32_e32 v52, 0xbfcc422a, v52
	v_rcp_f32_e32 v49, v49
	v_mul_f32_e32 v52, 0x3fb8aa3b, v52
	v_exp_f32_e32 v52, v52
	v_fma_f32 v48, v6, v72, v18
	v_lshlrev_b32_e32 v62, 16, v65
	v_fmac_f32_e32 v48, v10, v58
	v_fmac_f32_e32 v48, v14, v62
	v_mul_f32_e32 v49, v51, v49
	v_mul_f32_e32 v48, v48, v49
	v_add_f32_e32 v49, 1.0, v52
	v_rcp_f32_e32 v49, v49
	v_fma_f32 v51, v7, v69, v19
	v_and_b32_e32 v60, 0xffff0000, v65
	v_fmac_f32_e32 v51, v42, v56
	v_fmac_f32_e32 v51, v40, v60
	v_mul_f32_e32 v49, v50, v49
	v_mul_f32_e32 v49, v51, v49
	v_cvt_pk_bf16_f32 v50, v48, v49
	v_add_co_u32_e32 v48, vcc, 0x4326000, v46
	v_mov_b32_e32 v52, v62
	s_nop 0
	v_addc_co_u32_e32 v49, vcc, 0, v47, vcc
	v_mov_b32_e32 v53, v60
	v_mov_b32_e32 v54, v63
	v_mov_b32_e32 v55, v61
	ds_write_b32 v101, v50 offset:11776
	s_mov_b64 s[6:7], -1
	s_and_b64 vcc, exec, s[0:1]
	v_mov_b64_e32 v[48:49], v[54:55]
	v_mov_b64_e32 v[50:51], v[52:53]
	s_cbranch_vccnz .LBB0_807
	s_add_i32 s6, s84, 14
	s_and_b32 s6, s6, 0x7fe
	v_mov_b32_e32 v64, v62
	v_mov_b32_e32 v65, v60
	v_mov_b32_e32 v66, v63
	v_mov_b32_e32 v67, v61
	s_cmpk_eq_i32 s6, 0x7fe
	s_mov_b64 s[6:7], -1
	v_mov_b64_e32 v[48:49], v[66:67]
	v_mov_b64_e32 v[50:51], v[64:65]
	s_cbranch_scc1 .LBB0_804
	v_mov_b32_e32 v48, v63
	v_mov_b32_e32 v49, v61
	v_mov_b32_e32 v50, v62
	v_mov_b32_e32 v51, v60
	s_mov_b64 s[6:7], 0

; __device__ __forceinline__ float bf2f(unsigned b) { return __uint_as_float(b << 16); }
; __device__ __forceinline__ unsigned pk2(float lo, float hi) { unsigned r; asm("v_cvt_pk_bf16_f32 %0, %1, %2" : "=v"(r) : "v"(lo), "v"(hi)); return r; }
; __device__ __forceinline__ float gelu_t(float x) { return x * __builtin_amdgcn_rcpf(1.f + __expf(-1.5957691216057308f * (x + 0.044715f * x * x * x))); }
; __device__ __forceinline__ void act_item(int item, u16* UP, const u16* HALO, const float* sconv, const float* wconv, const float* bconv, float* out, int lane) {
;     ...
;         for (int t = 0; t < 16; ++t) {
;             const int row = rb * 64 + tb + t;
;             if (sample && (t & 3) == 0) { const int ns = (row - TP) >> 2; const float* s0 = sconv + (size_t)ns * 2 * FF2;
;                 const f32x2 a = *(const f32x2*)(s0 + j0), b = *(const f32x2*)(s0 + FF + j0), c = *(const f32x2*)(s0 + FF2 + j0), dd = *(const f32x2*)(s0 + FF2 + FF + j0);
;                 g2[0] = a.x; g2[1] = a.y; v2[0] = b.x; v2[1] = b.y; g1[0] = c.x; g1[1] = c.y; v1[0] = dd.x; v1[1] = dd.y; }
;             const float g0[2] = {bf2f(gw[t] & 0xffffu), bf2f(gw[t] >> 16)}, v0[2] = {bf2f(vw[t] & 0xffffu), bf2f(vw[t] >> 16)};
;             float res[2];
; #pragma unroll
;             for (int p = 0; p < 2; ++p) { const float cgv = bg[p] + wgt[0][p] * g2[p] + wgt[1][p] * g1[p] + wgt[2][p] * g0[p];
;                 const float cvv = bv[p] + wvl[0][p] * v2[p] + wvl[1][p] * v1[p] + wvl[2][p] * v0[p]; res[p] = gelu_t(cgv) * cvv;
;                 g2[p] = g1[p]; g1[p] = g0[p]; v2[p] = v1[p]; v1[p] = v0[p]; }
;             *(unsigned*)(UP + (size_t)row * FF2 + j0) = pk2(res[0], res[1]);
;             if (!sample) { const int tq = row & 2047; if (tq >= 2046) { float* o = out + O_CONVP + ((size_t)(row >> 11) * 2 + (tq - 2046)) * FF2;
;                     *(f32x2*)(o + j0) = (f32x2){g0[0], g0[1]}; *(f32x2*)(o + FF + j0) = (f32x2){v0[0], v0[1]}; } }
;             else if ((t & 3) >= 2) { const int ns = (row - TP) >> 2; float* o = out + O_CONVS + ((size_t)ns * 2 + ((t & 3) - 2)) * FF2;
;                     *(f32x2*)(o + j0) = (f32x2){g0[0], g0[1]}; *(f32x2*)(o + FF + j0) = (f32x2){v0[0], v0[1]}; }
.LBB0_809:
	v_lshlrev_b32_e32 v54, 16, v68
	v_and_b32_e32 v55, 0xffff0000, v68
	v_pk_fma_f32 v[58:59], v[26:27], v[58:59], v[24:25]
	v_pk_fma_f32 v[56:57], v[34:35], v[56:57], v[32:33]
	v_lshlrev_b32_e32 v65, 16, v1
	v_mov_b32_e32 v64, v54
	v_and_b32_e32 v53, 0xffff0000, v1
	v_mov_b32_e32 v52, v55
	v_pk_fma_f32 v[58:59], v[28:29], v[62:63], v[58:59]
	v_pk_fma_f32 v[56:57], v[36:37], v[60:61], v[56:57]
	v_pk_fma_f32 v[58:59], v[30:31], v[64:65], v[58:59]
	v_pk_fma_f32 v[56:57], v[38:39], v[52:53], v[56:57]
	v_mul_f32_e32 v1, 0x3d372713, v59
	v_mul_f32_e32 v52, 0x3d372713, v57
	v_mul_f32_e32 v1, v59, v1
	v_mul_f32_e32 v52, v57, v52
	v_fma_f32 v1, v59, v1, v59
	v_fma_f32 v52, v57, v52, v57
	v_mul_f32_e32 v1, 0xbfcc422a, v1
	v_mul_f32_e32 v52, 0xbfcc422a, v52
	v_mul_f32_e32 v1, 0x3fb8aa3b, v1
	v_mul_f32_e32 v52, 0x3fb8aa3b, v52
	v_exp_f32_e32 v1, v1
	v_exp_f32_e32 v52, v52
	v_add_co_u32_e32 v46, vcc, 0x4329000, v46
	v_add_f32_e32 v1, 1.0, v1
	v_add_f32_e32 v52, 1.0, v52
	v_rcp_f32_e32 v1, v1
	v_rcp_f32_e32 v52, v52
	v_addc_co_u32_e32 v47, vcc, 0, v47, vcc
	v_mul_f32_e32 v1, v59, v1
	v_mul_f32_e32 v52, v57, v52
	v_mul_f32_e32 v1, v58, v1
	v_mul_f32_e32 v56, v56, v52
	v_mov_b32_e32 v52, v65
	s_and_b64 vcc, exec, s[0:1]
	v_cvt_pk_bf16_f32 v1, v1, v56
	ds_write_b32 v101, v1 offset:12032
	s_cbranch_vccnz .LBB0_814
	s_add_i32 s85, s82, s83
	s_add_i32 s0, s85, 15
	s_mov_b64 s[6:7], 0
	s_cmpk_gt_u32 s0, 0x7fd
	s_mov_b64 s[68:69], 0
	s_cbranch_scc0 .LBB0_815
	s_addk_i32 s85, 0xf811
	s_add_u32 s0, s62, s85
	s_addc_u32 s1, s63, 0
	s_mulk_i32 s1, 0x5800
	s_mul_hi_u32 s68, s0, 0x5800
	s_add_i32 s68, s68, s1
	s_mulk_i32 s0, 0x5800
	s_add_u32 s0, s3, s0
	s_addc_u32 s1, s21, s68
	v_lshl_add_u64 v[46:47], v[2:3], 2, s[0:1]
	s_add_u32 s0, s0, 0x2c00
	global_store_dwordx2 v[46:47], v[52:53], off
	s_addc_u32 s1, s1, 0
	s_mov_b64 s[68:69], -1
	s_branch .LBB0_815
